# v077: v076 + diff fast path: P(t+1) bf16 converts of the last two k-chunks moved into the first P.V(t+1) MFMA gaps
# speedup vs baseline: 1.0005x; 1.0005x over previous
; #define LAS __attribute__((address_space(3)))
; template <int DQK, int DKA, int DV> ...
;     ...
;         if (64 * t <= qlast) {
;             f32x16 p0, p1; s16x4 vlo[8], vhi[8]; bf16x8 pf[4];
;             LAS const unsigned char* vb = lds + C::VOFF + (t & 3) * C::VBYTES + voff;
;             __builtin_amdgcn_sched_barrier(0);
;             __builtin_amdgcn_s_setprio(3);
; #pragma unroll
;             for (int d0 = 0; d0 < ND; ++d0) {
;                 if (d0 == 0) { p0 = MFMA32(kf[0], qr[0], negm); p1 = MFMA32(kf[1], qr[0], negm); }
;                 else { p0 = MFMA32(kf[2 * d0], qr[d0], p0); p1 = MFMA32(kf[2 * d0 + 1], qr[d0], p1); }
;             }
;             __builtin_amdgcn_s_setprio(0);
;             __builtin_amdgcn_sched_barrier(0);
;             ATT_VFRAG(0);
;             __builtin_amdgcn_sched_barrier(0);
;             if (64 * t + 63 > q0 + 32 * wid) {
;                 const int kvb = 64 * t + 4 * hi;
; #pragma unroll
;                 for (int i = 0; i < 16; ++i) { const int kv = kvb + (i & 3) + 8 * (i >> 2); if (kv > qabs) p0[i] = -INFINITY; if (kv + 32 > qabs) p1[i] = -INFINITY; }
;             }
;             float mxa = MAX3F(p0[0], p0[1], p1[0]), mxb = MAX3F(p0[2], p0[3], p1[1]); mxa = MAX3F(mxa, p1[2], p1[3]);
; #pragma unroll
;             for (int i = 4; i < 16; i += 4) { mxa = MAX3F(mxa, p0[i], p0[i + 1]); mxb = MAX3F(mxb, p0[i + 2], p0[i + 3]); mxa = MAX3F(mxa, p1[i], p1[i + 1]); mxb = MAX3F(mxb, p1[i + 2], p1[i + 3]); }
;             float mx = fmaxf(mxa, mxb);
;             { auto rr = __builtin_amdgcn_permlane32_swap(__float_as_uint(mx), __float_as_uint(mx), false, false); mx = fmaxf(__uint_as_float(rr[0]), __uint_as_float(rr[1])); }
;             if (!NEGM) mx -= m;
;             if (t == 0) {
;                 m = mx;
;                 if (NEGM) {
; #pragma unroll
;                     for (int i = 0; i < 16; ++i) { p0[i] -= mx; p1[i] -= mx; }
; #pragma unroll
;                     for (int i = 0; i < 16; ++i) negm[i] = -m;
;                 }
;             } else if (__any(mx > RESC_THR)) {
;     ...
;             { float rs = 0.f;
; #pragma unroll
;               for (int i = 0; i < 16; ++i) { p0[i] = __builtin_amdgcn_exp2f(NEGM ? p0[i] : p0[i] - m); p1[i] = __builtin_amdgcn_exp2f(NEGM ? p1[i] : p1[i] - m); rs += p0[i] + p1[i]; }
;               l += rs;
; #pragma unroll
;               for (int s = 0; s < 2; ++s) { u32x4 w0, w1;
.Lfast_d_qk:
	v_mfma_f32_32x32x16_bf16 v[80:95], v[144:147], v[112:115], v[0:15]
	ds_read_b128 v[144:147], v249
	v_mfma_f32_32x32x16_bf16 v[96:111], v[152:155], v[112:115], v[0:15]
	ds_read_b128 v[152:155], v249 offset:4608
	v_mfma_f32_32x32x16_bf16 v[80:95], v[140:143], v[116:119], v[80:95]
	ds_read_b128 v[140:143], v249 offset:32
	v_mfma_f32_32x32x16_bf16 v[96:111], v[148:151], v[116:119], v[96:111]
	ds_read_b128 v[148:151], v249 offset:4640
	v_mfma_f32_32x32x16_bf16 v[80:95], v[156:159], v[120:123], v[80:95]
	ds_read_b128 v[156:159], v249 offset:64
	v_mfma_f32_32x32x16_bf16 v[96:111], v[168:171], v[120:123], v[96:111]
	ds_read_b128 v[168:171], v249 offset:4672
	v_mfma_f32_32x32x16_bf16 v[80:95], v[160:163], v[124:127], v[80:95]
	ds_read_b128 v[160:163], v249 offset:96
	v_mfma_f32_32x32x16_bf16 v[96:111], v[164:167], v[124:127], v[96:111]
	ds_read_b128 v[164:167], v249 offset:4704
	s_setprio 0
	s_add_i32 s80, s1, -1
	s_add_i32 s23, s1, -2
	s_and_b32 s22, s80, 3
	s_mulk_i32 s22, 0x2400
	v_add_u32_e32 v253, s22, v217
	s_waitcnt vmcnt(0)
	ds_write_b128 v253, v[128:131]
	s_and_b32 s22, s23, 3
	s_mulk_i32 s22, 0x5000
	v_add_u32_e32 v253, s22, v227
	ds_write_b128 v253, v[132:135] offset:36864
	ds_write_b128 v253, v[136:139] offset:47104
	global_load_dwordx4 v[128:131], v[218:219], off
	v_add_co_u32_e32 v254, vcc, 0x2000, v220
	s_nop 1
	v_addc_co_u32_e32 v255, vcc, 0, v221, vcc
	global_load_dwordx4 v[132:135], v[220:221], off
	global_load_dwordx4 v[136:139], v[254:255], off
	v_max_f32_e32 v232, v81, v81
	v_max_f32_e32 v233, v80, v80
	v_max_f32_e32 v232, v233, v232
	v_max3_f32 v233, v82, v83, v97
	v_max3_f32 v232, v232, v96, v98
	v_max3_f32 v232, v232, v99, v84
	v_max3_f32 v233, v233, v86, v87
	v_max3_f32 v232, v232, v85, v100
	v_max3_f32 v233, v233, v102, v103
	v_max3_f32 v232, v232, v101, v88
	v_max3_f32 v233, v233, v90, v91
	v_max3_f32 v232, v232, v89, v104
	v_max3_f32 v233, v233, v106, v107
	v_max3_f32 v232, v232, v105, v92
	v_max3_f32 v233, v233, v94, v95
	v_max3_f32 v232, v232, v93, v108
	v_max3_f32 v233, v233, v110, v111
	v_max3_f32 v232, v232, v109, v233
	v_mov_b32_e32 v233, v232
	s_nop 1
	v_permlane32_swap_b32_e32 v232, v233
	v_max_f32_e32 v233, v233, v233
	v_max_f32_e32 v232, v232, v232
	v_max_f32_e32 v232, v232, v233
	v_cmp_lt_f32_e32 vcc, s62, v232
	s_cbranch_vccnz .Lfast_d_bail1
	s_waitcnt lgkmcnt(0)
	v_exp_f32_e32 v80, v80
	v_exp_f32_e32 v96, v96
	v_exp_f32_e32 v81, v81
	v_exp_f32_e32 v97, v97
	v_mfma_f32_32x32x16_bf16 v[172:187], v[144:147], v[112:115], v[0:15]
	ds_read_b64_tr_b16 v[144:145], v210 offset:36864
	ds_read_b64_tr_b16 v[146:147], v210 offset:39424
	v_exp_f32_e32 v82, v82
	v_exp_f32_e32 v98, v98
	v_exp_f32_e32 v83, v83
	v_exp_f32_e32 v99, v99
	v_mfma_f32_32x32x16_bf16 v[188:203], v[152:155], v[112:115], v[0:15]
	ds_read_b64_tr_b16 v[152:153], v210 offset:36928
	ds_read_b64_tr_b16 v[154:155], v210 offset:39488
	v_exp_f32_e32 v84, v84
	v_exp_f32_e32 v100, v100
	v_exp_f32_e32 v85, v85
	v_exp_f32_e32 v101, v101
	v_mfma_f32_32x32x16_bf16 v[172:187], v[140:143], v[116:119], v[172:187]
	ds_read_b64_tr_b16 v[140:141], v210 offset:41984
	ds_read_b64_tr_b16 v[142:143], v210 offset:44544
	v_exp_f32_e32 v86, v86
	v_exp_f32_e32 v102, v102
	v_exp_f32_e32 v87, v87
	v_exp_f32_e32 v103, v103
	v_mfma_f32_32x32x16_bf16 v[188:203], v[148:151], v[116:119], v[188:203]
	ds_read_b64_tr_b16 v[148:149], v210 offset:42048
	ds_read_b64_tr_b16 v[150:151], v210 offset:44608
	v_exp_f32_e32 v88, v88
	v_exp_f32_e32 v104, v104
	v_exp_f32_e32 v89, v89
	v_exp_f32_e32 v105, v105
	v_mfma_f32_32x32x16_bf16 v[172:187], v[156:159], v[120:123], v[172:187]
	ds_read_b64_tr_b16 v[156:157], v210 offset:47104
	ds_read_b64_tr_b16 v[158:159], v210 offset:49664
	v_exp_f32_e32 v90, v90
	v_exp_f32_e32 v106, v106
	v_exp_f32_e32 v91, v91
	v_exp_f32_e32 v107, v107
	v_mfma_f32_32x32x16_bf16 v[188:203], v[168:171], v[120:123], v[188:203]
	ds_read_b64_tr_b16 v[168:169], v210 offset:47168
	ds_read_b64_tr_b16 v[170:171], v210 offset:49728
	v_exp_f32_e32 v92, v92
	v_exp_f32_e32 v108, v108
	v_exp_f32_e32 v93, v93
	v_exp_f32_e32 v109, v109
	v_mfma_f32_32x32x16_bf16 v[172:187], v[160:163], v[124:127], v[172:187]
	ds_read_b64_tr_b16 v[160:161], v210 offset:52224
	ds_read_b64_tr_b16 v[162:163], v210 offset:54784
	v_exp_f32_e32 v94, v94
	v_exp_f32_e32 v110, v110
	v_exp_f32_e32 v95, v95
	v_exp_f32_e32 v111, v111
	v_mfma_f32_32x32x16_bf16 v[188:203], v[164:167], v[124:127], v[188:203]
	ds_read_b64_tr_b16 v[164:165], v210 offset:52288
	ds_read_b64_tr_b16 v[166:167], v210 offset:54848
	v_cvt_pk_bf16_f32 v232, v80, v81
	v_cvt_pk_bf16_f32 v233, v82, v83
	v_cvt_pk_bf16_f32 v234, v84, v85
	v_cvt_pk_bf16_f32 v235, v86, v87
	v_cvt_pk_bf16_f32 v236, v96, v97
	v_cvt_pk_bf16_f32 v237, v98, v99
	v_cvt_pk_bf16_f32 v238, v100, v101
	v_cvt_pk_bf16_f32 v239, v102, v103
	v_cvt_pk_bf16_f32 v240, v88, v89
	v_cvt_pk_bf16_f32 v241, v90, v91
	v_cvt_pk_bf16_f32 v242, v92, v93
	v_cvt_pk_bf16_f32 v243, v94, v95
	v_cvt_pk_bf16_f32 v244, v104, v105
	v_cvt_pk_bf16_f32 v245, v106, v107
	v_cvt_pk_bf16_f32 v246, v108, v109
	v_cvt_pk_bf16_f32 v247, v110, v111
	v_max_f32_e32 v250, v173, v173
	v_max_f32_e32 v251, v172, v172
	v_max_f32_e32 v250, v251, v250
	v_max3_f32 v251, v174, v175, v189
	v_max3_f32 v250, v250, v188, v190
	v_max3_f32 v250, v250, v191, v176
	v_max3_f32 v251, v251, v178, v179
	v_max3_f32 v250, v250, v177, v192
	v_max3_f32 v251, v251, v194, v195
	v_max3_f32 v250, v250, v193, v180
	v_max3_f32 v251, v251, v182, v183
	v_max3_f32 v250, v250, v181, v196
	v_max3_f32 v251, v251, v198, v199
	v_max3_f32 v250, v250, v197, v184
	v_max3_f32 v251, v251, v186, v187
	v_max3_f32 v250, v250, v185, v200
	v_max3_f32 v251, v251, v202, v203
	v_max3_f32 v250, v250, v201, v251
	v_mov_b32_e32 v251, v250
	s_nop 1
	v_permlane32_swap_b32_e32 v250, v251
	v_max_f32_e32 v251, v251, v251
	v_max_f32_e32 v250, v250, v250
	v_max_f32_e32 v250, v250, v251
	v_cmp_lt_f32_e32 vcc, s62, v250
	s_cbranch_vccnz .Lfast_d_bail2
; __device__ __forceinline__ unsigned cvtpk_s(float lo, float hi) { f32x2_t v = {lo, hi}; bf16x2_t b = __builtin_convertvector(v, bf16x2_t); return __builtin_bit_cast(unsigned, b); }
; #define ATT_KFRAG(slot) do { LAS const unsigned char* kb_ = lds + (slot) * C::KBYTES + koff; \
;     _Pragma("unroll") for (int d0 = 0; d0 < ND; ++d0) { kf[2 * d0] = *(LAS const bf16x8*)(kb_ + 32 * d0); kf[2 * d0 + 1] = *(LAS const bf16x8*)(kb_ + 32 * KP + 32 * d0); } } while (0)
; #define ATT_VFRAG(vv) do { _Pragma("unroll") for (int j = 0; j < 2; ++j) _Pragma("unroll") for (int s4 = 0; s4 < 4; ++s4) { \
;         vlo[j * 4 + s4] = vtr(vb + (16 * s4) * VP + 64 * ((vv) + j)); vhi[j * 4 + s4] = vtr(vb + (16 * s4 + 8) * VP + 64 * ((vv) + j)); } } while (0)
; template <int DQK, int DKA, int DV> ...
;     ...
;             { float rs = 0.f;
; #pragma unroll
;               for (int i = 0; i < 16; ++i) { p0[i] = __builtin_amdgcn_exp2f(NEGM ? p0[i] : p0[i] - m); p1[i] = __builtin_amdgcn_exp2f(NEGM ? p1[i] : p1[i] - m); rs += p0[i] + p1[i]; }
;               l += rs;
; #pragma unroll
;               for (int s = 0; s < 2; ++s) { u32x4 w0, w1;
;                 w0.x = cvtpk_s(p0[8 * s], p0[8 * s + 1]); w0.y = cvtpk_s(p0[8 * s + 2], p0[8 * s + 3]); w0.z = cvtpk_s(p0[8 * s + 4], p0[8 * s + 5]); w0.w = cvtpk_s(p0[8 * s + 6], p0[8 * s + 7]);
;                 w1.x = cvtpk_s(p1[8 * s], p1[8 * s + 1]); w1.y = cvtpk_s(p1[8 * s + 2], p1[8 * s + 3]); w1.z = cvtpk_s(p1[8 * s + 4], p1[8 * s + 5]); w1.w = cvtpk_s(p1[8 * s + 6], p1[8 * s + 7]);
;                 pf[s] = __builtin_bit_cast(bf16x8, w0); pf[2 + s] = __builtin_bit_cast(bf16x8, w1); } }
;             __builtin_amdgcn_sched_barrier(0);
;             if (NV == 2) {
;                 __builtin_amdgcn_s_setprio(3); ATT_PV(0); __builtin_amdgcn_s_setprio(0);
;                 __builtin_amdgcn_sched_barrier(0);
;                 if (t + 1 < NT) ATT_KFRAG(ks1);
;             } else {
;                 __builtin_amdgcn_s_setprio(3); ATT_PV(0); __builtin_amdgcn_s_setprio(0);
;                 __builtin_amdgcn_sched_barrier(0);
;                 ATT_VFRAG(2);
;                 __builtin_amdgcn_sched_barrier(0);
;                 __builtin_amdgcn_s_setprio(3); ATT_PV(2); __builtin_amdgcn_s_setprio(0);
;                 __builtin_amdgcn_sched_barrier(0);
;                 if (t + 1 < NT) ATT_KFRAG(ks1);
;             }
	s_setprio 0
	s_waitcnt lgkmcnt(0)
	v_mfma_f32_32x32x16_bf16 v[32:47], v[144:147], v[232:235], v[32:47]
	v_lshl_add_u64 v[218:219], v[218:219], 0, s[10:11]
	v_lshl_add_u64 v[220:221], v[220:221], 0, s[8:9]
	s_add_i32 s23, s1, -1
	s_and_b32 s22, s1, 3
	s_mulk_i32 s22, 0x2400
	v_add_u32_e32 v253, s22, v217
	s_waitcnt vmcnt(0)
	ds_write_b128 v253, v[128:131]
	s_and_b32 s22, s23, 3
	s_mulk_i32 s22, 0x5000
	v_mfma_f32_32x32x16_bf16 v[16:31], v[152:155], v[232:235], v[16:31]
	v_add_u32_e32 v253, s22, v227
	ds_write_b128 v253, v[132:135] offset:36864
	ds_write_b128 v253, v[136:139] offset:47104
	global_load_dwordx4 v[128:131], v[218:219], off
	v_add_co_u32_e32 v254, vcc, 0x2000, v220
	s_nop 1
	v_addc_co_u32_e32 v255, vcc, 0, v221, vcc
	global_load_dwordx4 v[132:135], v[220:221], off
	global_load_dwordx4 v[136:139], v[254:255], off
	v_add_f32_e32 v80, v80, v96
	v_add_f32_e32 v81, v81, v97
	v_add_f32_e32 v80, 0, v80
	v_add_f32_e32 v82, v82, v98
	v_mfma_f32_32x32x16_bf16 v[32:47], v[140:143], v[240:243], v[32:47]
	v_add_f32_e32 v80, v81, v80
	v_add_f32_e32 v83, v83, v99
	v_add_f32_e32 v80, v82, v80
	v_add_f32_e32 v84, v84, v100
	v_add_f32_e32 v80, v83, v80
	v_add_f32_e32 v85, v85, v101
	v_add_f32_e32 v80, v84, v80
	v_add_f32_e32 v86, v86, v102
	v_add_f32_e32 v80, v85, v80
	v_add_f32_e32 v87, v87, v103
	v_mfma_f32_32x32x16_bf16 v[16:31], v[148:151], v[240:243], v[16:31]
	v_add_f32_e32 v80, v86, v80
	v_add_f32_e32 v88, v88, v104
	v_add_f32_e32 v80, v87, v80
	v_add_f32_e32 v89, v89, v105
	v_add_f32_e32 v80, v88, v80
	v_add_f32_e32 v90, v90, v106
	v_add_f32_e32 v80, v89, v80
	v_add_f32_e32 v91, v91, v107
	v_add_f32_e32 v80, v90, v80
	v_add_f32_e32 v92, v92, v108
	v_mfma_f32_32x32x16_bf16 v[32:47], v[156:159], v[236:239], v[32:47]
	v_add_f32_e32 v80, v91, v80
	v_add_f32_e32 v93, v93, v109
	v_add_f32_e32 v80, v92, v80
	v_add_f32_e32 v94, v94, v110
	v_add_f32_e32 v80, v93, v80
	v_add_f32_e32 v95, v95, v111
	v_add_f32_e32 v80, v94, v80
	v_add_f32_e32 v80, v95, v80
	v_add_f32_e32 v231, v231, v80
	ds_read_b64_tr_b16 v[80:81], v210 offset:36992
	ds_read_b64_tr_b16 v[82:83], v210 offset:39552
	ds_read_b64_tr_b16 v[84:85], v210 offset:37056
	ds_read_b64_tr_b16 v[86:87], v210 offset:39616
	v_mfma_f32_32x32x16_bf16 v[16:31], v[168:171], v[236:239], v[16:31]
	ds_read_b64_tr_b16 v[88:89], v210 offset:42112
	ds_read_b64_tr_b16 v[90:91], v210 offset:44672
	ds_read_b64_tr_b16 v[92:93], v210 offset:42176
	ds_read_b64_tr_b16 v[94:95], v210 offset:44736
	ds_read_b64_tr_b16 v[96:97], v210 offset:47232
	ds_read_b64_tr_b16 v[98:99], v210 offset:49792
	ds_read_b64_tr_b16 v[100:101], v210 offset:47296
	ds_read_b64_tr_b16 v[102:103], v210 offset:49856
	v_mfma_f32_32x32x16_bf16 v[32:47], v[160:163], v[244:247], v[32:47]
	ds_read_b64_tr_b16 v[104:105], v210 offset:52352
	ds_read_b64_tr_b16 v[106:107], v210 offset:54912
	ds_read_b64_tr_b16 v[108:109], v210 offset:52416
	ds_read_b64_tr_b16 v[110:111], v210 offset:54976
	v_exp_f32_e32 v172, v172
	v_exp_f32_e32 v188, v188
	v_mfma_f32_32x32x16_bf16 v[16:31], v[164:167], v[244:247], v[16:31]
	v_exp_f32_e32 v173, v173
	v_exp_f32_e32 v189, v189
	v_exp_f32_e32 v174, v174
	v_exp_f32_e32 v190, v190
	s_waitcnt lgkmcnt(14)
	v_mfma_f32_32x32x16_bf16 v[64:79], v[80:83], v[232:235], v[64:79]
	ds_read_b64_tr_b16 v[144:145], v252 offset:36864
	ds_read_b64_tr_b16 v[146:147], v252 offset:39424
	v_exp_f32_e32 v175, v175
	v_exp_f32_e32 v191, v191
	v_exp_f32_e32 v176, v176
	v_exp_f32_e32 v192, v192
	s_waitcnt lgkmcnt(14)
	v_mfma_f32_32x32x16_bf16 v[48:63], v[84:87], v[232:235], v[48:63]
	ds_read_b64_tr_b16 v[152:153], v252 offset:36928
	ds_read_b64_tr_b16 v[154:155], v252 offset:39488
	v_exp_f32_e32 v177, v177
	v_exp_f32_e32 v193, v193
	v_exp_f32_e32 v178, v178
	v_exp_f32_e32 v194, v194
	s_waitcnt lgkmcnt(14)
	v_mfma_f32_32x32x16_bf16 v[64:79], v[88:91], v[240:243], v[64:79]
	ds_read_b64_tr_b16 v[140:141], v252 offset:41984
	ds_read_b64_tr_b16 v[142:143], v252 offset:44544
	v_exp_f32_e32 v179, v179
	v_exp_f32_e32 v195, v195
	v_exp_f32_e32 v180, v180
	s_waitcnt lgkmcnt(14)
	v_mfma_f32_32x32x16_bf16 v[48:63], v[92:95], v[240:243], v[48:63]
	ds_read_b64_tr_b16 v[148:149], v252 offset:42048
	ds_read_b64_tr_b16 v[150:151], v252 offset:44608
	v_exp_f32_e32 v196, v196
	v_exp_f32_e32 v181, v181
	v_exp_f32_e32 v197, v197
	s_waitcnt lgkmcnt(14)
	v_mfma_f32_32x32x16_bf16 v[64:79], v[96:99], v[236:239], v[64:79]
	ds_read_b64_tr_b16 v[156:157], v252 offset:47104
	ds_read_b64_tr_b16 v[158:159], v252 offset:49664
	v_exp_f32_e32 v182, v182
	v_exp_f32_e32 v198, v198
	v_exp_f32_e32 v183, v183
	s_waitcnt lgkmcnt(14)
	v_mfma_f32_32x32x16_bf16 v[48:63], v[100:103], v[236:239], v[48:63]
	ds_read_b64_tr_b16 v[168:169], v252 offset:47168
	ds_read_b64_tr_b16 v[170:171], v252 offset:49728
	v_exp_f32_e32 v199, v199
	v_exp_f32_e32 v184, v184
	v_exp_f32_e32 v200, v200
	s_waitcnt lgkmcnt(14)
; __device__ __forceinline__ unsigned cvtpk_s(float lo, float hi) { f32x2_t v = {lo, hi}; bf16x2_t b = __builtin_convertvector(v, bf16x2_t); return __builtin_bit_cast(unsigned, b); }
; #define ATT_KFRAG(slot) do { LAS const unsigned char* kb_ = lds + (slot) * C::KBYTES + koff; \
;     _Pragma("unroll") for (int d0 = 0; d0 < ND; ++d0) { kf[2 * d0] = *(LAS const bf16x8*)(kb_ + 32 * d0); kf[2 * d0 + 1] = *(LAS const bf16x8*)(kb_ + 32 * KP + 32 * d0); } } while (0)
; #define ATT_VFRAG(vv) do { _Pragma("unroll") for (int j = 0; j < 2; ++j) _Pragma("unroll") for (int s4 = 0; s4 < 4; ++s4) { \
;         vlo[j * 4 + s4] = vtr(vb + (16 * s4) * VP + 64 * ((vv) + j)); vhi[j * 4 + s4] = vtr(vb + (16 * s4 + 8) * VP + 64 * ((vv) + j)); } } while (0)
; template <int DQK, int DKA, int DV> ...
;     ...
;             { float rs = 0.f;
; #pragma unroll
;               for (int i = 0; i < 16; ++i) { p0[i] = __builtin_amdgcn_exp2f(NEGM ? p0[i] : p0[i] - m); p1[i] = __builtin_amdgcn_exp2f(NEGM ? p1[i] : p1[i] - m); rs += p0[i] + p1[i]; }
;               l += rs;
; #pragma unroll
;               for (int s = 0; s < 2; ++s) { u32x4 w0, w1;
;                 w0.x = cvtpk_s(p0[8 * s], p0[8 * s + 1]); w0.y = cvtpk_s(p0[8 * s + 2], p0[8 * s + 3]); w0.z = cvtpk_s(p0[8 * s + 4], p0[8 * s + 5]); w0.w = cvtpk_s(p0[8 * s + 6], p0[8 * s + 7]);
;                 w1.x = cvtpk_s(p1[8 * s], p1[8 * s + 1]); w1.y = cvtpk_s(p1[8 * s + 2], p1[8 * s + 3]); w1.z = cvtpk_s(p1[8 * s + 4], p1[8 * s + 5]); w1.w = cvtpk_s(p1[8 * s + 6], p1[8 * s + 7]);
;                 pf[s] = __builtin_bit_cast(bf16x8, w0); pf[2 + s] = __builtin_bit_cast(bf16x8, w1); } }
;             __builtin_amdgcn_sched_barrier(0);
;             if (NV == 2) {
;                 __builtin_amdgcn_s_setprio(3); ATT_PV(0); __builtin_amdgcn_s_setprio(0);
;                 __builtin_amdgcn_sched_barrier(0);
;                 if (t + 1 < NT) ATT_KFRAG(ks1);
;             } else {
;                 __builtin_amdgcn_s_setprio(3); ATT_PV(0); __builtin_amdgcn_s_setprio(0);
;                 __builtin_amdgcn_sched_barrier(0);
;                 ATT_VFRAG(2);
;                 __builtin_amdgcn_sched_barrier(0);
;                 __builtin_amdgcn_s_setprio(3); ATT_PV(2); __builtin_amdgcn_s_setprio(0);
;                 __builtin_amdgcn_sched_barrier(0);
;                 if (t + 1 < NT) ATT_KFRAG(ks1);
;             }
	v_mfma_f32_32x32x16_bf16 v[64:79], v[104:107], v[244:247], v[64:79]
	ds_read_b64_tr_b16 v[160:161], v252 offset:52224
	ds_read_b64_tr_b16 v[162:163], v252 offset:54784
	v_exp_f32_e32 v185, v185
	v_exp_f32_e32 v201, v201
	v_exp_f32_e32 v186, v186
	s_waitcnt lgkmcnt(14)
	v_mfma_f32_32x32x16_bf16 v[48:63], v[108:111], v[244:247], v[48:63]
	ds_read_b64_tr_b16 v[164:165], v252 offset:52288
	ds_read_b64_tr_b16 v[166:167], v252 offset:54848
	v_exp_f32_e32 v202, v202
	v_exp_f32_e32 v187, v187
	v_exp_f32_e32 v203, v203
	s_setprio 0
	v_cvt_pk_bf16_f32 v232, v172, v173
	v_cvt_pk_bf16_f32 v233, v174, v175
	v_cvt_pk_bf16_f32 v234, v176, v177
	v_cvt_pk_bf16_f32 v235, v178, v179
	v_cvt_pk_bf16_f32 v240, v180, v181
	v_cvt_pk_bf16_f32 v241, v182, v183
	v_cvt_pk_bf16_f32 v242, v184, v185
	v_cvt_pk_bf16_f32 v243, v186, v187
	s_waitcnt lgkmcnt(0)
	v_mfma_f32_32x32x16_bf16 v[32:47], v[144:147], v[232:235], v[32:47]
	ds_read_b64_tr_b16 v[80:81], v252 offset:36992
	ds_read_b64_tr_b16 v[82:83], v252 offset:39552
	ds_read_b64_tr_b16 v[84:85], v252 offset:37056
	ds_read_b64_tr_b16 v[86:87], v252 offset:39616
	v_cvt_pk_bf16_f32 v236, v188, v189
	v_cvt_pk_bf16_f32 v237, v190, v191
	v_add_f32_e32 v172, v172, v188
	v_mfma_f32_32x32x16_bf16 v[16:31], v[152:155], v[232:235], v[16:31]
	ds_read_b64_tr_b16 v[88:89], v252 offset:42112
	ds_read_b64_tr_b16 v[90:91], v252 offset:44672
	ds_read_b64_tr_b16 v[92:93], v252 offset:42176
	ds_read_b64_tr_b16 v[94:95], v252 offset:44736
	v_cvt_pk_bf16_f32 v238, v192, v193
	v_cvt_pk_bf16_f32 v239, v194, v195
	v_add_f32_e32 v173, v173, v189
	v_mfma_f32_32x32x16_bf16 v[32:47], v[140:143], v[240:243], v[32:47]
	ds_read_b64_tr_b16 v[96:97], v252 offset:47232
	ds_read_b64_tr_b16 v[98:99], v252 offset:49792
	ds_read_b64_tr_b16 v[100:101], v252 offset:47296
	ds_read_b64_tr_b16 v[102:103], v252 offset:49856
	v_cvt_pk_bf16_f32 v244, v196, v197
	v_cvt_pk_bf16_f32 v245, v198, v199
	v_add_f32_e32 v172, 0, v172
	v_mfma_f32_32x32x16_bf16 v[16:31], v[148:151], v[240:243], v[16:31]
	ds_read_b64_tr_b16 v[104:105], v252 offset:52352
	ds_read_b64_tr_b16 v[106:107], v252 offset:54912
	ds_read_b64_tr_b16 v[108:109], v252 offset:52416
	ds_read_b64_tr_b16 v[110:111], v252 offset:54976
	v_cvt_pk_bf16_f32 v246, v200, v201
	v_cvt_pk_bf16_f32 v247, v202, v203
	v_add_f32_e32 v174, v174, v190
	v_mfma_f32_32x32x16_bf16 v[32:47], v[156:159], v[236:239], v[32:47]
	v_add_f32_e32 v172, v173, v172
	v_add_f32_e32 v175, v175, v191
	v_add_f32_e32 v172, v174, v172
	v_mfma_f32_32x32x16_bf16 v[16:31], v[168:171], v[236:239], v[16:31]
	v_add_f32_e32 v176, v176, v192
	v_add_f32_e32 v172, v175, v172
	v_add_f32_e32 v177, v177, v193
	v_mfma_f32_32x32x16_bf16 v[32:47], v[160:163], v[244:247], v[32:47]
	v_add_f32_e32 v172, v176, v172
	v_add_f32_e32 v178, v178, v194
	v_add_f32_e32 v172, v177, v172
	v_mfma_f32_32x32x16_bf16 v[16:31], v[164:167], v[244:247], v[16:31]
	v_add_f32_e32 v179, v179, v195
	v_add_f32_e32 v172, v178, v172
	v_add_f32_e32 v180, v180, v196
	s_add_i32 s1, s1, 2
	s_addk_i32 s79, 0x80
	s_add_i32 s22, s1, -4
	s_and_b32 s22, s22, 3
	s_mulk_i32 s22, 0x2400
	v_add_u32_e32 v249, s22, v226
	s_waitcnt lgkmcnt(0)
	v_mfma_f32_32x32x16_bf16 v[64:79], v[80:83], v[232:235], v[64:79]
	ds_read_b128 v[144:147], v249
	ds_read_b128 v[152:155], v249 offset:4608
	v_add_f32_e32 v172, v179, v172
	v_add_f32_e32 v181, v181, v197
	v_add_f32_e32 v172, v180, v172
	v_mfma_f32_32x32x16_bf16 v[48:63], v[84:87], v[232:235], v[48:63]
	ds_read_b128 v[140:143], v249 offset:32
	ds_read_b128 v[148:151], v249 offset:4640
	v_add_f32_e32 v182, v182, v198
	v_add_f32_e32 v172, v181, v172
	v_add_f32_e32 v183, v183, v199
	v_mfma_f32_32x32x16_bf16 v[64:79], v[88:91], v[240:243], v[64:79]
	ds_read_b128 v[156:159], v249 offset:64
	ds_read_b128 v[168:171], v249 offset:4672
	v_add_f32_e32 v172, v182, v172
	v_add_f32_e32 v184, v184, v200
	v_add_f32_e32 v172, v183, v172
	v_mfma_f32_32x32x16_bf16 v[48:63], v[92:95], v[240:243], v[48:63]
	ds_read_b128 v[160:163], v249 offset:96
	ds_read_b128 v[164:167], v249 offset:4704
	v_add_f32_e32 v185, v185, v201
	v_add_f32_e32 v172, v184, v172
	v_add_f32_e32 v186, v186, v202
	v_mfma_f32_32x32x16_bf16 v[64:79], v[96:99], v[236:239], v[64:79]
	v_add_f32_e32 v172, v185, v172
	v_add_f32_e32 v187, v187, v203
	v_add_f32_e32 v172, v186, v172
	v_lshl_add_u64 v[218:219], v[218:219], 0, s[10:11]
	v_mfma_f32_32x32x16_bf16 v[48:63], v[100:103], v[236:239], v[48:63]
	v_add_f32_e32 v172, v187, v172
	v_add_f32_e32 v231, v231, v172
	v_lshl_add_u64 v[220:221], v[220:221], 0, s[8:9]
	v_mfma_f32_32x32x16_bf16 v[64:79], v[104:107], v[244:247], v[64:79]
	v_mfma_f32_32x32x16_bf16 v[48:63], v[108:111], v[244:247], v[48:63]
	s_setprio 0
	s_add_i32 s23, s1, 1
	s_cmp_lt_u32 s23, s16
	s_cbranch_scc0 .Lfast_d_x
	s_add_i32 s50, s1, -4
	s_and_b32 s22, s50, 3
	s_mulk_i32 s22, 0x5000
	v_add_u32_e32 v210, s22, v229
	s_add_i32 s51, s1, -3
	s_and_b32 s22, s51, 3
	s_mul_i32 s23, s22, 0x5000
	s_mulk_i32 s22, 0x2400
	v_add_u32_e32 v249, s22, v226
	v_add_u32_e32 v252, s23, v229
	s_waitcnt lgkmcnt(0)
	s_barrier
	s_setprio 3
	s_branch .Lfast_d_qk
